# P9 K-loop: s_setprio toggles removed (both wave groups at equal priority)
# speedup vs baseline: 1.0120x; 1.0120x over previous
; #define PG8_STAGE(bufoff, gbase, voff) do { _Pragma("unroll") for (int _i = 0; _i < 2; ++_i) \
;         __builtin_amdgcn_global_load_lds((const unsigned*)((const char*)(gbase) + (voff)[_i]), (LAS unsigned*)(lds + (bufoff) + ldsw + _i * 8192), 16, 0, 0); } while (0)
; #define PG8_LDA(dst, b, h) do { _Pragma("unroll") for (int m = 0; m < 4; ++m) _Pragma("unroll") for (int k = 0; k < 2; ++k) dst[m][k] = *(const LAS bf16x8*)(lds + PG8_SA(b, h) + aoff + m * 2048 + k * 1024); } while (0)
; #define PG8_LDB(dst, b, h) do { _Pragma("unroll") for (int n = 0; n < 2; ++n) _Pragma("unroll") for (int k = 0; k < 2; ++k) dst[n][k] = *(const LAS bf16x8*)(lds + PG8_SB(b, h) + boff + n * 2048 + k * 1024); } while (0)
; #define PG8_MMA(ai, bj, At, Bt) do { __builtin_amdgcn_s_setprio(1); _Pragma("unroll") for (int m = 0; m < 4; ++m) _Pragma("unroll") for (int n = 0; n < 2; ++n) _Pragma("unroll") for (int k = 0; k < 2; ++k) \
;         acc[ai][bj][m][n] = __builtin_amdgcn_mfma_f32_16x16x32_bf16(Bt[n][k], At[m][k], acc[ai][bj][m][n], 0, 0, 0); __builtin_amdgcn_s_setprio(0); } while (0)
; #define PG8_WAIT_V(n) asm volatile("s_waitcnt vmcnt(" #n ")" ::: "memory")
; #define PG8_WAIT_L(n) asm volatile("s_waitcnt lgkmcnt(" #n ")" ::: "memory")
; #define PG8_BAR __builtin_amdgcn_s_barrier()
; #define PG8_SCHED __builtin_amdgcn_sched_barrier(0)
; template <class Epi, class Sched, bool ALIGN_EPI = true, bool SP2 = true>
; __device__ __forceinline__ void gemm_phase(LAS unsigned char* lds, const Gemm g, const Sched& S, const Epi& E) {
;     ...
;             const char* a1 = cA + (size_t)(t + 1) * kstep;
;             const char* a2 = last ? nA : cA + (size_t)(t + 2) * kstep; const char* b2 = last ? nB : cB + (size_t)(t + 2) * kstep;
;             const char* a3 = a2 + kstep; const char* b3 = b2 + kstep;
;             if (last && has_next) S.a_ready(nxt);
;             if constexpr (SP2) {
;             PG8_LDB(B0, 0, 0); PG8_LDB(B1, 0, 1); PG8_SCHED; PG8_LDA(At, 0, 0); PG8_STAGE(PG8_SA(1, 1), a1 + hstep, voffA);
;             PG8_WAIT_V(8); PG8_WAIT_L(0); PG8_BAR; PG8_MMA(0, 0, At, B0); PG8_MMA(0, 1, At, B1); PG8_BAR; PG8_SCHED;
;             PG8_LDA(At, 0, 1); PG8_STAGE(PG8_SB(0, 0), b2, voffB); PG8_STAGE(PG8_SB(0, 1), b2 + hstep, voffB); PG8_STAGE(PG8_SA(0, 0), a2, voffA);
;             PG8_WAIT_V(8); PG8_WAIT_L(0); PG8_BAR; PG8_MMA(1, 0, At, B0); PG8_MMA(1, 1, At, B1); PG8_BAR; PG8_SCHED;
.LBB0_1810:
	ds_read_b128 v[148:151], v168
	ds_read_b128 v[152:155], v168 offset:1024
	ds_read_b128 v[156:159], v168 offset:2048
	ds_read_b128 v[160:163], v168 offset:3072
	ds_read_b128 v[174:177], v169
	ds_read_b128 v[178:181], v169 offset:1024
	ds_read_b128 v[182:185], v169 offset:2048
	ds_read_b128 v[186:189], v169 offset:3072
	s_add_u32 s30, s4, 0xfff00080
	s_addc_u32 s31, s5, -1
	s_cmp_eq_u32 s56, 60
	s_cselect_b32 s35, s25, s31
	s_cselect_b32 s34, s52, s30
	s_cselect_b32 s31, s23, s55
	s_cselect_b32 s30, s53, s54
	s_add_i32 m0, s40, 0xc000
	ds_read_b128 v[190:193], v170
	ds_read_b128 v[194:197], v170 offset:1024
	ds_read_b128 v[198:201], v170 offset:2048
	ds_read_b128 v[202:205], v170 offset:3072
	ds_read_b128 v[206:209], v170 offset:4096
	ds_read_b128 v[210:213], v170 offset:5120
	ds_read_b128 v[214:217], v170 offset:6144
	ds_read_b128 v[218:221], v170 offset:7168
	global_load_lds_dwordx4 v140, s[4:5]
	s_add_i32 m0, s40, 0xe000
	s_nop 0
	global_load_lds_dwordx4 v142, s[4:5]
	s_waitcnt vmcnt(8)
	s_waitcnt lgkmcnt(0)
	s_barrier
	v_mfma_f32_16x16x32_bf16 v[126:129], v[148:151], v[190:193], v[126:129]
	v_mfma_f32_16x16x32_bf16 v[122:125], v[156:159], v[190:193], v[122:125]
	v_mfma_f32_16x16x32_bf16 v[106:109], v[156:159], v[198:201], v[106:109]
	v_mfma_f32_16x16x32_bf16 v[110:113], v[148:151], v[198:201], v[110:113]
	v_mfma_f32_16x16x32_bf16 v[94:97], v[148:151], v[206:209], v[94:97]
	v_mfma_f32_16x16x32_bf16 v[90:93], v[156:159], v[206:209], v[90:93]
	v_mfma_f32_16x16x32_bf16 v[74:77], v[156:159], v[214:217], v[74:77]
	v_mfma_f32_16x16x32_bf16 v[78:81], v[148:151], v[214:217], v[78:81]
	v_mfma_f32_16x16x32_bf16 v[126:129], v[152:155], v[194:197], v[126:129]
	v_mfma_f32_16x16x32_bf16 v[122:125], v[160:163], v[194:197], v[122:125]
	v_mfma_f32_16x16x32_bf16 v[106:109], v[160:163], v[202:205], v[106:109]
	v_mfma_f32_16x16x32_bf16 v[110:113], v[152:155], v[202:205], v[110:113]
	v_mfma_f32_16x16x32_bf16 v[94:97], v[152:155], v[210:213], v[94:97]
	v_mfma_f32_16x16x32_bf16 v[90:93], v[160:163], v[210:213], v[90:93]
	v_mfma_f32_16x16x32_bf16 v[74:77], v[160:163], v[218:221], v[74:77]
	v_mfma_f32_16x16x32_bf16 v[78:81], v[152:155], v[218:221], v[78:81]
	v_mfma_f32_16x16x32_bf16 v[118:121], v[174:177], v[190:193], v[118:121]
	v_mfma_f32_16x16x32_bf16 v[114:117], v[182:185], v[190:193], v[114:117]
	v_mfma_f32_16x16x32_bf16 v[98:101], v[182:185], v[198:201], v[98:101]
	v_mfma_f32_16x16x32_bf16 v[102:105], v[174:177], v[198:201], v[102:105]
	v_mfma_f32_16x16x32_bf16 v[86:89], v[174:177], v[206:209], v[86:89]
	v_mfma_f32_16x16x32_bf16 v[82:85], v[182:185], v[206:209], v[82:85]
	v_mfma_f32_16x16x32_bf16 v[66:69], v[182:185], v[214:217], v[66:69]
	v_mfma_f32_16x16x32_bf16 v[70:73], v[174:177], v[214:217], v[70:73]
	v_mfma_f32_16x16x32_bf16 v[118:121], v[178:181], v[194:197], v[118:121]
	v_mfma_f32_16x16x32_bf16 v[114:117], v[186:189], v[194:197], v[114:117]
	v_mfma_f32_16x16x32_bf16 v[98:101], v[186:189], v[202:205], v[98:101]
	v_mfma_f32_16x16x32_bf16 v[102:105], v[178:181], v[202:205], v[102:105]
	v_mfma_f32_16x16x32_bf16 v[86:89], v[178:181], v[210:213], v[86:89]
	v_mfma_f32_16x16x32_bf16 v[82:85], v[186:189], v[210:213], v[82:85]
	v_mfma_f32_16x16x32_bf16 v[66:69], v[186:189], v[218:221], v[66:69]
	v_mfma_f32_16x16x32_bf16 v[70:73], v[178:181], v[218:221], v[70:73]
	s_barrier
	s_add_i32 s57, s48, s37
	v_lshl_add_u64 v[164:165], s[30:31], 0, v[134:135]
	s_mov_b32 m0, s57
	ds_read_b128 v[190:193], v170 offset:16384
	ds_read_b128 v[194:197], v170 offset:17408
	ds_read_b128 v[198:201], v170 offset:18432
	ds_read_b128 v[202:205], v170 offset:19456
	ds_read_b128 v[206:209], v170 offset:20480
	ds_read_b128 v[210:213], v170 offset:21504
	ds_read_b128 v[214:217], v170 offset:22528
	ds_read_b128 v[218:221], v170 offset:23552
	global_load_lds_dwordx4 v[164:165], off
	s_add_i32 m0, s57, 0x2000
	s_add_u32 s58, s30, 0x100000
	v_lshl_add_u64 v[222:223], s[30:31], 0, v[130:131]
	s_addc_u32 s59, s31, 0
	s_add_i32 s57, s49, s37
	global_load_lds_dwordx4 v[222:223], off
	s_mov_b32 m0, s57
	v_lshl_add_u64 v[226:227], s[34:35], 0, v[132:133]
	global_load_lds_dwordx4 v134, s[58:59]
	s_add_i32 m0, s57, 0x2000
	s_nop 0
	global_load_lds_dwordx4 v130, s[58:59]
	v_lshl_add_u64 v[224:225], s[34:35], 0, v[136:137]
	s_mov_b32 m0, s40
	s_nop 0
	global_load_lds_dwordx4 v[224:225], off
	s_mov_b32 m0, s41
	s_nop 0
	global_load_lds_dwordx4 v[226:227], off
	s_waitcnt vmcnt(8)
	s_waitcnt lgkmcnt(0)
	s_barrier
	v_mfma_f32_16x16x32_bf16 v[62:65], v[148:151], v[190:193], v[62:65]
	v_mfma_f32_16x16x32_bf16 v[58:61], v[156:159], v[190:193], v[58:61]
	v_mfma_f32_16x16x32_bf16 v[42:45], v[156:159], v[198:201], v[42:45]
	v_mfma_f32_16x16x32_bf16 v[46:49], v[148:151], v[198:201], v[46:49]
	v_mfma_f32_16x16x32_bf16 v[30:33], v[148:151], v[206:209], v[30:33]
	v_mfma_f32_16x16x32_bf16 v[26:29], v[156:159], v[206:209], v[26:29]
	v_mfma_f32_16x16x32_bf16 v[10:13], v[156:159], v[214:217], v[10:13]
	v_mfma_f32_16x16x32_bf16 v[14:17], v[148:151], v[214:217], v[14:17]
	v_mfma_f32_16x16x32_bf16 v[62:65], v[152:155], v[194:197], v[62:65]
	v_mfma_f32_16x16x32_bf16 v[58:61], v[160:163], v[194:197], v[58:61]
	v_mfma_f32_16x16x32_bf16 v[42:45], v[160:163], v[202:205], v[42:45]
	v_mfma_f32_16x16x32_bf16 v[46:49], v[152:155], v[202:205], v[46:49]
	v_mfma_f32_16x16x32_bf16 v[30:33], v[152:155], v[210:213], v[30:33]
	v_mfma_f32_16x16x32_bf16 v[26:29], v[160:163], v[210:213], v[26:29]
	v_mfma_f32_16x16x32_bf16 v[10:13], v[160:163], v[218:221], v[10:13]
	v_mfma_f32_16x16x32_bf16 v[14:17], v[152:155], v[218:221], v[14:17]
	v_mfma_f32_16x16x32_bf16 v[54:57], v[174:177], v[190:193], v[54:57]
	v_mfma_f32_16x16x32_bf16 v[50:53], v[182:185], v[190:193], v[50:53]
	v_mfma_f32_16x16x32_bf16 v[34:37], v[182:185], v[198:201], v[34:37]
	v_mfma_f32_16x16x32_bf16 v[38:41], v[174:177], v[198:201], v[38:41]
	v_mfma_f32_16x16x32_bf16 v[22:25], v[174:177], v[206:209], v[22:25]
	v_mfma_f32_16x16x32_bf16 v[18:21], v[182:185], v[206:209], v[18:21]
	v_mfma_f32_16x16x32_bf16 v[2:5], v[182:185], v[214:217], v[2:5]
	v_mfma_f32_16x16x32_bf16 v[6:9], v[174:177], v[214:217], v[6:9]
	v_mfma_f32_16x16x32_bf16 v[54:57], v[178:181], v[194:197], v[54:57]
	v_mfma_f32_16x16x32_bf16 v[50:53], v[186:189], v[194:197], v[50:53]
	v_mfma_f32_16x16x32_bf16 v[34:37], v[186:189], v[202:205], v[34:37]
	v_mfma_f32_16x16x32_bf16 v[38:41], v[178:181], v[202:205], v[38:41]
	v_mfma_f32_16x16x32_bf16 v[22:25], v[178:181], v[210:213], v[22:25]
	v_mfma_f32_16x16x32_bf16 v[18:21], v[186:189], v[210:213], v[18:21]
	v_mfma_f32_16x16x32_bf16 v[2:5], v[186:189], v[218:221], v[2:5]
	v_mfma_f32_16x16x32_bf16 v[6:9], v[178:181], v[218:221], v[6:9]
	s_barrier
; #define PG8_STAGE(bufoff, gbase, voff) do { _Pragma("unroll") for (int _i = 0; _i < 2; ++_i) \
;         __builtin_amdgcn_global_load_lds((const unsigned*)((const char*)(gbase) + (voff)[_i]), (LAS unsigned*)(lds + (bufoff) + ldsw + _i * 8192), 16, 0, 0); } while (0)
; #define PG8_LDA(dst, b, h) do { _Pragma("unroll") for (int m = 0; m < 4; ++m) _Pragma("unroll") for (int k = 0; k < 2; ++k) dst[m][k] = *(const LAS bf16x8*)(lds + PG8_SA(b, h) + aoff + m * 2048 + k * 1024); } while (0)
; #define PG8_LDB(dst, b, h) do { _Pragma("unroll") for (int n = 0; n < 2; ++n) _Pragma("unroll") for (int k = 0; k < 2; ++k) dst[n][k] = *(const LAS bf16x8*)(lds + PG8_SB(b, h) + boff + n * 2048 + k * 1024); } while (0)
; #define PG8_MMA(ai, bj, At, Bt) do { __builtin_amdgcn_s_setprio(1); _Pragma("unroll") for (int m = 0; m < 4; ++m) _Pragma("unroll") for (int n = 0; n < 2; ++n) _Pragma("unroll") for (int k = 0; k < 2; ++k) \
;         acc[ai][bj][m][n] = __builtin_amdgcn_mfma_f32_16x16x32_bf16(Bt[n][k], At[m][k], acc[ai][bj][m][n], 0, 0, 0); __builtin_amdgcn_s_setprio(0); } while (0)
; #define PG8_WAIT_V(n) asm volatile("s_waitcnt vmcnt(" #n ")" ::: "memory")
; #define PG8_WAIT_L(n) asm volatile("s_waitcnt lgkmcnt(" #n ")" ::: "memory")
; #define PG8_BAR __builtin_amdgcn_s_barrier()
; #define PG8_SCHED __builtin_amdgcn_sched_barrier(0)
; template <class Epi, class Sched, bool ALIGN_EPI = true, bool SP2 = true>
; __device__ __forceinline__ void gemm_phase(LAS unsigned char* lds, const Gemm g, const Sched& S, const Epi& E) {
;     ...
;         for (int t = 0; t < nt; t += 2) {
;     ...
;             PG8_LDB(B0, 1, 0); PG8_LDB(B1, 1, 1); PG8_SCHED; PG8_LDA(At, 1, 0); PG8_STAGE(PG8_SA(0, 1), a2 + hstep, voffA);
;             PG8_WAIT_V(8); PG8_WAIT_L(0); PG8_BAR; PG8_MMA(0, 0, At, B0); PG8_MMA(0, 1, At, B1); PG8_BAR; PG8_SCHED;
;             PG8_LDA(At, 1, 1); PG8_STAGE(PG8_SB(1, 0), b3, voffB); PG8_STAGE(PG8_SB(1, 1), b3 + hstep, voffB); PG8_STAGE(PG8_SA(1, 0), a3, voffA);
;             PG8_WAIT_V(8); PG8_WAIT_L(0); PG8_BAR; PG8_MMA(1, 0, At, B0); PG8_MMA(1, 1, At, B1); PG8_BAR; PG8_SCHED;
	s_add_i32 s57, 0, 0x18000
	s_add_i32 s58, 0, 0x1c000
	v_add_u32_e32 v160, s57, v167
	v_add_u32_e32 v173, s58, v167
	ds_read_b128 v[148:151], v160
	ds_read_b128 v[152:155], v160 offset:1024
	ds_read_b128 v[156:159], v160 offset:2048
	ds_read_b128 v[160:163], v160 offset:3072
	ds_read_b128 v[174:177], v173
	ds_read_b128 v[178:181], v173 offset:1024
	ds_read_b128 v[182:185], v173 offset:2048
	ds_read_b128 v[186:189], v173 offset:3072
	s_add_u32 s34, s34, 0x100000
	s_addc_u32 s35, s35, 0
	s_mov_b32 m0, s42
	ds_read_b128 v[190:193], v170 offset:32768
	ds_read_b128 v[194:197], v170 offset:33792
	ds_read_b128 v[198:201], v170 offset:34816
	ds_read_b128 v[202:205], v170 offset:35840
	ds_read_b128 v[206:209], v170 offset:36864
	ds_read_b128 v[210:213], v170 offset:37888
	ds_read_b128 v[214:217], v170 offset:38912
	ds_read_b128 v[218:221], v170 offset:39936
	global_load_lds_dwordx4 v136, s[34:35]
	s_mov_b32 m0, s43
	s_nop 0
	global_load_lds_dwordx4 v132, s[34:35]
	s_waitcnt vmcnt(8)
	s_waitcnt lgkmcnt(0)
	s_barrier
	v_mfma_f32_16x16x32_bf16 v[126:129], v[148:151], v[190:193], v[126:129]
	v_mfma_f32_16x16x32_bf16 v[122:125], v[156:159], v[190:193], v[122:125]
	v_mfma_f32_16x16x32_bf16 v[106:109], v[156:159], v[198:201], v[106:109]
	v_mfma_f32_16x16x32_bf16 v[110:113], v[148:151], v[198:201], v[110:113]
	v_mfma_f32_16x16x32_bf16 v[94:97], v[148:151], v[206:209], v[94:97]
	v_mfma_f32_16x16x32_bf16 v[90:93], v[156:159], v[206:209], v[90:93]
	v_mfma_f32_16x16x32_bf16 v[74:77], v[156:159], v[214:217], v[74:77]
	v_mfma_f32_16x16x32_bf16 v[78:81], v[148:151], v[214:217], v[78:81]
	v_mfma_f32_16x16x32_bf16 v[126:129], v[152:155], v[194:197], v[126:129]
	v_mfma_f32_16x16x32_bf16 v[122:125], v[160:163], v[194:197], v[122:125]
	v_mfma_f32_16x16x32_bf16 v[106:109], v[160:163], v[202:205], v[106:109]
	v_mfma_f32_16x16x32_bf16 v[110:113], v[152:155], v[202:205], v[110:113]
	v_mfma_f32_16x16x32_bf16 v[94:97], v[152:155], v[210:213], v[94:97]
	v_mfma_f32_16x16x32_bf16 v[90:93], v[160:163], v[210:213], v[90:93]
	v_mfma_f32_16x16x32_bf16 v[74:77], v[160:163], v[218:221], v[74:77]
	v_mfma_f32_16x16x32_bf16 v[78:81], v[152:155], v[218:221], v[78:81]
	v_mfma_f32_16x16x32_bf16 v[118:121], v[174:177], v[190:193], v[118:121]
	v_mfma_f32_16x16x32_bf16 v[114:117], v[182:185], v[190:193], v[114:117]
	v_mfma_f32_16x16x32_bf16 v[98:101], v[182:185], v[198:201], v[98:101]
	v_mfma_f32_16x16x32_bf16 v[102:105], v[174:177], v[198:201], v[102:105]
	v_mfma_f32_16x16x32_bf16 v[86:89], v[174:177], v[206:209], v[86:89]
	v_mfma_f32_16x16x32_bf16 v[82:85], v[182:185], v[206:209], v[82:85]
	v_mfma_f32_16x16x32_bf16 v[66:69], v[182:185], v[214:217], v[66:69]
	v_mfma_f32_16x16x32_bf16 v[70:73], v[174:177], v[214:217], v[70:73]
	v_mfma_f32_16x16x32_bf16 v[118:121], v[178:181], v[194:197], v[118:121]
	v_mfma_f32_16x16x32_bf16 v[114:117], v[186:189], v[194:197], v[114:117]
	v_mfma_f32_16x16x32_bf16 v[98:101], v[186:189], v[202:205], v[98:101]
	v_mfma_f32_16x16x32_bf16 v[102:105], v[178:181], v[202:205], v[102:105]
	v_mfma_f32_16x16x32_bf16 v[86:89], v[178:181], v[210:213], v[86:89]
	v_mfma_f32_16x16x32_bf16 v[82:85], v[186:189], v[210:213], v[82:85]
	v_mfma_f32_16x16x32_bf16 v[66:69], v[186:189], v[218:221], v[66:69]
	v_mfma_f32_16x16x32_bf16 v[70:73], v[178:181], v[218:221], v[70:73]
	s_barrier
	s_add_i32 s34, s57, s37
	v_lshl_add_u64 v[164:165], v[164:165], 0, s[18:19]
	s_mov_b32 m0, s34
	ds_read_b128 v[190:193], v170 offset:49152
	ds_read_b128 v[194:197], v170 offset:50176
	ds_read_b128 v[198:201], v170 offset:51200
	ds_read_b128 v[202:205], v170 offset:52224
	ds_read_b128 v[206:209], v170 offset:53248
	ds_read_b128 v[210:213], v170 offset:54272
	ds_read_b128 v[214:217], v170 offset:55296
	ds_read_b128 v[218:221], v170 offset:56320
	global_load_lds_dwordx4 v[164:165], off
	s_add_i32 m0, s34, 0x2000
	s_add_u32 s30, s30, 0x100080
	v_lshl_add_u64 v[164:165], v[222:223], 0, s[18:19]
	s_addc_u32 s31, s31, 0
	s_add_i32 s34, s58, s37
	global_load_lds_dwordx4 v[164:165], off
	s_mov_b32 m0, s34
	s_nop 0
	global_load_lds_dwordx4 v134, s[30:31]
	s_add_i32 m0, s34, 0x2000
	s_nop 0
	global_load_lds_dwordx4 v130, s[30:31]
	v_lshl_add_u64 v[164:165], v[224:225], 0, s[18:19]
	s_mov_b32 m0, s45
	s_nop 0
	global_load_lds_dwordx4 v[164:165], off
	v_lshl_add_u64 v[164:165], v[226:227], 0, s[18:19]
	s_mov_b32 m0, s46
	s_nop 0
	global_load_lds_dwordx4 v[164:165], off
	s_waitcnt vmcnt(8)
	s_waitcnt lgkmcnt(0)
	s_barrier
	v_mfma_f32_16x16x32_bf16 v[62:65], v[148:151], v[190:193], v[62:65]
	v_mfma_f32_16x16x32_bf16 v[58:61], v[156:159], v[190:193], v[58:61]
	v_mfma_f32_16x16x32_bf16 v[42:45], v[156:159], v[198:201], v[42:45]
	v_mfma_f32_16x16x32_bf16 v[46:49], v[148:151], v[198:201], v[46:49]
	v_mfma_f32_16x16x32_bf16 v[30:33], v[148:151], v[206:209], v[30:33]
	v_mfma_f32_16x16x32_bf16 v[26:29], v[156:159], v[206:209], v[26:29]
	v_mfma_f32_16x16x32_bf16 v[10:13], v[156:159], v[214:217], v[10:13]
	v_mfma_f32_16x16x32_bf16 v[14:17], v[148:151], v[214:217], v[14:17]
	v_mfma_f32_16x16x32_bf16 v[62:65], v[152:155], v[194:197], v[62:65]
	v_mfma_f32_16x16x32_bf16 v[58:61], v[160:163], v[194:197], v[58:61]
	v_mfma_f32_16x16x32_bf16 v[42:45], v[160:163], v[202:205], v[42:45]
	v_mfma_f32_16x16x32_bf16 v[46:49], v[152:155], v[202:205], v[46:49]
	v_mfma_f32_16x16x32_bf16 v[30:33], v[152:155], v[210:213], v[30:33]
	v_mfma_f32_16x16x32_bf16 v[26:29], v[160:163], v[210:213], v[26:29]
	v_mfma_f32_16x16x32_bf16 v[10:13], v[160:163], v[218:221], v[10:13]
	v_mfma_f32_16x16x32_bf16 v[14:17], v[152:155], v[218:221], v[14:17]
	v_mfma_f32_16x16x32_bf16 v[54:57], v[174:177], v[190:193], v[54:57]
	v_mfma_f32_16x16x32_bf16 v[50:53], v[182:185], v[190:193], v[50:53]
	v_mfma_f32_16x16x32_bf16 v[34:37], v[182:185], v[198:201], v[34:37]
	v_mfma_f32_16x16x32_bf16 v[38:41], v[174:177], v[198:201], v[38:41]
	v_mfma_f32_16x16x32_bf16 v[22:25], v[174:177], v[206:209], v[22:25]
	v_mfma_f32_16x16x32_bf16 v[18:21], v[182:185], v[206:209], v[18:21]
	v_mfma_f32_16x16x32_bf16 v[2:5], v[182:185], v[214:217], v[2:5]
	v_mfma_f32_16x16x32_bf16 v[6:9], v[174:177], v[214:217], v[6:9]
	v_mfma_f32_16x16x32_bf16 v[54:57], v[178:181], v[194:197], v[54:57]
	v_mfma_f32_16x16x32_bf16 v[50:53], v[186:189], v[194:197], v[50:53]
	v_mfma_f32_16x16x32_bf16 v[34:37], v[186:189], v[202:205], v[34:37]
	v_mfma_f32_16x16x32_bf16 v[38:41], v[178:181], v[202:205], v[38:41]
	v_mfma_f32_16x16x32_bf16 v[22:25], v[178:181], v[210:213], v[22:25]
	v_mfma_f32_16x16x32_bf16 v[18:21], v[186:189], v[210:213], v[18:21]
	v_mfma_f32_16x16x32_bf16 v[2:5], v[186:189], v[218:221], v[2:5]
	v_mfma_f32_16x16x32_bf16 v[6:9], v[178:181], v[218:221], v[6:9]
	s_barrier
	s_add_i32 s56, s56, 2
	s_add_u32 s4, s4, 0x100
	s_addc_u32 s5, s5, 0
	s_add_u32 s54, s54, 0x100
	s_addc_u32 s55, s55, 0
	s_cmp_gt_u32 s56, 61
	s_cbranch_scc0 .LBB0_1810
	s_and_b64 vcc, exec, s[20:21]
	s_cbranch_vccz .LBB0_1813
	s_barrier
